# first grid barrier: cooperative-groups grid sync replaced by the same two-level XCD barrier the other 17 phase seams use
# baseline (speedup 1.0000x reference)
;   __syncthreads();
;   if (threadIdx.x == 0) {
;     __threadfence();
;     const unsigned nb = gridDim.x;
;     const unsigned ng = (nb & 7u) == 0u ? 8u : 1u, grp = ng == 8u ? (blockIdx.x & 7u) : 0u, per = nb / ng;
;     const unsigned gen = __hip_atomic_load(st + 32 * 9, __ATOMIC_RELAXED, __HIP_MEMORY_SCOPE_AGENT);
;     if (__hip_atomic_fetch_add(st + 32 * grp, 1u, __ATOMIC_RELAXED, __HIP_MEMORY_SCOPE_AGENT) == per - 1u) {
;       __hip_atomic_store(st + 32 * grp, 0u, __ATOMIC_RELAXED, __HIP_MEMORY_SCOPE_AGENT);
;       if (__hip_atomic_fetch_add(st + 32 * 8, 1u, __ATOMIC_RELEASE, __HIP_MEMORY_SCOPE_AGENT) == ng - 1u) {
.LBB0_110:
	s_or_b64 exec, exec, s[10:11]
	s_mov_b64 s[10:11], s[62:63]
	v_cmp_eq_u32_e64 s[2:3], 0, v210
	s_waitcnt lgkmcnt(0)
	s_barrier
	v_writelane_b32 v248, s2, 4
	s_nop 1
	v_writelane_b32 v248, s3, 5
	s_and_saveexec_b64 s[0:1], s[2:3]
	s_cbranch_execz .Lgb0_172
	v_mov_b32_e32 v0, 0x1e798000
	buffer_wbl2 sc1
	s_waitcnt vmcnt(0)
	buffer_inv sc1
	global_load_dword v0, v0, s[10:11] offset:1152 sc1
	v_readlane_b32 s3, v248, 3
	v_readlane_b32 s2, v248, 0
	s_lshl_b32 s3, s3, 5
	s_and_b32 s2, s2, 7
	s_and_b32 s3, s3, 0xe0
	s_cmp_eq_u32 s2, 0
	s_cselect_b64 s[6:7], -1, 0
	s_and_b64 s[4:5], s[6:7], exec
	s_cselect_b32 s2, s3, 0
	s_add_u32 s4, s10, 0x1e798480
	s_addc_u32 s5, s11, 0
	s_lshl_b32 s2, s2, 2
	s_mov_b64 s[8:9], exec
	s_add_u32 s2, s10, s2
	s_addc_u32 s3, s11, 0
	v_mbcnt_lo_u32_b32 v1, s8, 0
	s_add_u32 s12, s2, 0x1e798000
	v_mbcnt_hi_u32_b32 v1, s9, v1
	s_addc_u32 s13, s3, 0
	v_cmp_eq_u32_e32 vcc, 0, v1
	s_and_saveexec_b64 s[14:15], vcc
	s_cbranch_execz .Lgb0_163
	s_bcnt1_i32_b64 s2, s[8:9]
	v_mov_b32_e32 v2, 0
	v_mov_b32_e32 v3, s2
	global_atomic_add v2, v2, v3, s[12:13] sc0
